# barrier: XCD leader signals the top counter right after its write-back and polls top + invalidate-done together; same-XCD release word written by plain store (atomic generation word kept as fallback)
# speedup vs baseline: 1.1280x; 1.0077x over previous
.Lxb_w1:
	global_load_dword v3, v1, s[6:7] offset:128 sc1
	s_add_i32 s3, s3, 1
	s_waitcnt vmcnt(0)
	v_readfirstlane_b32 s24, v3
	s_cmp_ge_u32 s24, s22
	s_cbranch_scc1 .LBB0_19
	s_and_b32 s24, s3, 63
	s_cmp_lg_u32 s24, 0
	s_cbranch_scc1 .Lxb_w1
	global_load_dword v2, v1, s[6:7] sc1
	s_waitcnt vmcnt(0)
	v_readfirstlane_b32 s24, v2
	s_cmp_ge_u32 s24, s22
	s_cbranch_scc1 .LBB0_19
	s_bitcmp1_b32 s3, 16
	s_cbranch_scc0 .Lxb_w1
	s_branch .LBB0_19
.Lxb_lead:
	buffer_wbl2 sc1
	v_readlane_b32 s6, v244, 48
	v_readlane_b32 s7, v244, 49
	s_sub_i32 s27, s23, s22
	s_mul_i32 s23, s22, s21
	s_mov_b32 s3, 0
	s_nop 1
	s_waitcnt vmcnt(0)
	global_atomic_add v1, v158, s[6:7]
.Lxb_w3:
	global_load_dword v2, v1, s[6:7] sc1
	global_load_dword v3, v1, s[18:19] offset:128 sc1
	s_add_i32 s3, s3, 1
	s_waitcnt vmcnt(0)
	v_readfirstlane_b32 s24, v2
	v_readfirstlane_b32 s26, v3
	s_cmp_ge_u32 s24, s23
	s_cselect_b32 s24, 1, 0
	s_cmp_ge_u32 s26, s27
	s_cselect_b32 s24, s24, 0
	s_cmp_lg_u32 s24, 0
	s_cbranch_scc1 .Lxb_rel
	s_bitcmp1_b32 s3, 16
	s_cbranch_scc0 .Lxb_w3
.Lxb_rel:
	v_readlane_b32 s6, v244, 46
	v_readlane_b32 s7, v244, 47
	v_mov_b32_e32 v3, s22
	s_nop 4
	global_store_dword v1, v3, s[6:7] offset:128
	global_atomic_add v1, v158, s[6:7]
	s_branch .LBB0_19
